# phase balance: the 256 w_out_b transpose jobs stay in phase 0 instead of the scan-pass-2 phase (transposing blocks there now do 4 jobs, not 5)
# baseline (speedup 1.0000x reference)
.LBB0_9:
	s_add_i32 s80, s14, 0x520
	s_cmpk_lt_u32 s80, 0x400
	s_cselect_b64 s[2:3], -1, 0
	s_and_b64 s[2:3], s[8:9], s[2:3]
	s_and_b64 vcc, exec, s[2:3]
	s_cbranch_vccnz .LBB0_8
	s_add_i32 s79, s14, 0xa40
	s_cmpk_gt_i32 s79, 0x41f
	s_mov_b64 s[2:3], -1
	s_cbranch_scc0 .LBB0_56
	s_cmpk_gt_u32 s79, 0x51f
	s_cbranch_scc0 .LBB0_53
	s_cmpk_gt_u32 s79, 0x71f
	s_cbranch_scc0 .LBB0_40
	s_cmpk_gt_u32 s79, 0x91f
	s_cbranch_scc0 .LBB0_27
	s_cmpk_gt_i32 s79, 0xa1f
	s_cbranch_scc0 .LBB0_24
	s_cmpk_gt_u32 s79, 0xa2f
	s_cbranch_scc0 .LBB0_21
	s_cmpk_gt_u32 s79, 0xa3f
	s_cbranch_scc0 .LBB0_18
	s_bfe_u32 s70, s79, 0x10004
	s_and_b32 s71, s15, 0x3c0
	s_and_b32 s81, s10, 0x7fffffc0
	s_cmp_lt_u32 s14, 32
	s_cselect_b32 s2, 0x1000, s77
	s_cselect_b32 s46, s76, 0x3100
	s_add_u32 s2, s20, s2
	v_or_b32_e32 v2, s71, v148
	s_addc_u32 s3, s21, 0
	v_lshlrev_b32_e32 v3, 2, v2
	v_lshl_add_u64 v[62:63], v[12:13], 0, s[46:47]
	global_load_dword v44, v3, s[2:3]
	global_load_dword v61, v3, s[2:3] offset:64
	global_load_dword v69, v3, s[2:3] offset:128
	global_load_dword v71, v3, s[2:3] offset:192
	v_add_u32_e32 v6, s71, v1
	v_add_u32_e32 v8, s71, v15
	v_add_u32_e32 v10, s71, v19
	v_mad_u64_u32 v[2:3], s[2:3], v2, s78, v[62:63]
	v_mad_u64_u32 v[6:7], s[2:3], v6, s78, v[62:63]
	v_mad_u64_u32 v[40:41], s[2:3], v8, s78, v[62:63]
	v_mad_u64_u32 v[62:63], s[2:3], v10, s78, v[62:63]
	global_load_dwordx4 v[2:5], v[2:3], off
	s_nop 0
	global_load_dwordx4 v[6:9], v[6:7], off
	s_nop 0
	global_load_dwordx4 v[40:43], v[40:41], off
	s_cmp_eq_u32 s70, 0
	global_load_dwordx4 v[62:65], v[62:63], off
	s_cselect_b64 vcc, -1, 0
	v_add_u32_e32 v10, s81, v74
	v_lshlrev_b64 v[66:67], 12, v[10:11]
	v_lshl_add_u64 v[66:67], s[0:1], 0, v[66:67]
	s_lshl_b32 s46, s70, 11
	v_lshl_add_u64 v[66:67], v[66:67], 0, s[46:47]
	s_lshl_b32 s46, s71, 1
	v_lshlrev_b32_e32 v10, 1, v14
	v_lshl_add_u64 v[66:67], v[66:67], 0, s[46:47]
	v_lshl_add_u64 v[66:67], v[66:67], 0, v[10:11]
	s_mov_b64 s[2:3], 0
	s_waitcnt vmcnt(7)
	v_sub_f32_e32 v68, 1.0, v44
	s_waitcnt vmcnt(6)
	v_sub_f32_e32 v70, 1.0, v61
	s_waitcnt vmcnt(5)
	v_sub_f32_e32 v72, 1.0, v69
	s_waitcnt vmcnt(4)
	v_sub_f32_e32 v73, 1.0, v71
	v_cndmask_b32_e32 v44, v44, v68, vcc
	v_cndmask_b32_e32 v68, v61, v70, vcc
	v_cndmask_b32_e32 v70, v69, v72, vcc
	v_cndmask_b32_e32 v72, v71, v73, vcc
	s_waitcnt vmcnt(3)
	v_pk_mul_f32 v[2:3], v[2:3], v[44:45] op_sel_hi:[1,0]
	v_pk_mul_f32 v[4:5], v[4:5], v[44:45] op_sel_hi:[1,0]
	s_waitcnt vmcnt(2)
	v_pk_mul_f32 v[6:7], v[6:7], v[68:69] op_sel_hi:[1,0]
	v_pk_mul_f32 v[8:9], v[8:9], v[68:69] op_sel_hi:[1,0]
	s_waitcnt vmcnt(1)
	v_pk_mul_f32 v[40:41], v[40:41], v[70:71] op_sel_hi:[1,0]
	v_pk_mul_f32 v[42:43], v[42:43], v[70:71] op_sel_hi:[1,0]
	s_waitcnt vmcnt(0)
	v_pk_mul_f32 v[62:63], v[62:63], v[72:73] op_sel_hi:[1,0]
	v_pk_mul_f32 v[64:65], v[64:65], v[72:73] op_sel_hi:[1,0]
	ds_write2_b32 v48, v2, v3 offset1:1
	ds_write2_b32 v48, v4, v5 offset0:2 offset1:3
	ds_write2_b32 v49, v6, v7 offset1:1
	ds_write2_b32 v50, v8, v9 offset1:1
	ds_write2_b32 v51, v40, v41 offset1:1
	ds_write2_b32 v52, v42, v43 offset1:1
	ds_write2_b32 v53, v62, v63 offset1:1
	ds_write2_b32 v54, v64, v65 offset1:1
	s_waitcnt lgkmcnt(0)
	s_barrier
	ds_read2_b32 v[2:3], v21 offset1:130
	ds_read2_b32 v[4:5], v23 offset0:65 offset1:195
	ds_read2_b32 v[6:7], v55 offset0:4 offset1:134
	ds_read2_b32 v[8:9], v56 offset0:69 offset1:199
	ds_read2_b32 v[40:41], v57 offset0:8 offset1:138
	ds_read2_b32 v[42:43], v58 offset0:73 offset1:203
	ds_read2_b32 v[62:63], v59 offset0:12 offset1:142
	ds_read2_b32 v[64:65], v60 offset0:77 offset1:207
	s_waitcnt lgkmcnt(6)
	v_cvt_pk_bf16_f32 v2, v2, v4
	v_cvt_pk_bf16_f32 v3, v3, v5
	s_waitcnt lgkmcnt(4)
	v_cvt_pk_bf16_f32 v4, v6, v8
	v_cvt_pk_bf16_f32 v5, v7, v9
	s_waitcnt lgkmcnt(2)
	v_cvt_pk_bf16_f32 v6, v40, v42
	v_cvt_pk_bf16_f32 v7, v41, v43
	s_waitcnt lgkmcnt(0)
	v_cvt_pk_bf16_f32 v8, v62, v64
	v_cvt_pk_bf16_f32 v9, v63, v65
	global_store_dwordx4 v[66:67], v[2:5], off
	global_store_dwordx4 v[66:67], v[6:9], off offset:16
	s_barrier

.LBB0_692:
	s_or_b64 exec, exec, s[0:1]
	s_cmpk_gt_u32 s12, 0xff
	s_cselect_b64 s[0:1], -1, 0
	s_cmpk_lt_i32 s12, 0x500
	s_cselect_b64 s[2:3], -1, 0
	s_and_b64 s[0:1], s[0:1], s[2:3]
	s_and_b64 s[0:1], s[0:1], s[8:9]
	s_andn2_b64 vcc, exec, s[0:1]
	s_waitcnt lgkmcnt(0)
	s_barrier
	s_cbranch_vccnz .LBB0_726
	s_add_u32 s0, s56, 0x1300000
	s_addc_u32 s1, s57, 0
	s_add_u32 s4, s56, 0xf00000
	s_addc_u32 s5, s57, 0
	s_add_u32 s8, s56, 0xb00000
	v_and_b32_e32 v0, 48, v150
	s_addc_u32 s9, s57, 0
	s_add_i32 s10, s58, 0xffffff00
	v_and_b32_e32 v8, 0xf0, v150
	v_mul_u32_u24_e32 v4, 0x41, v0
	s_cmp_lg_u64 s[62:63], 0
	v_add_u32_e32 v1, 16, v8
	v_mul_u32_u24_e32 v2, 0x104, v148
	v_and_b32_e32 v3, 0x3fc, v196
	v_lshlrev_b32_e32 v4, 2, v4
	s_cselect_b64 s[24:25], -1, 0
	s_cmp_lg_u64 s[48:49], 0
	v_add3_u32 v26, 16, v3, v4
	v_add3_u32 v27, 16, v4, v3
	v_mov_b32_e32 v9, 0
	s_cselect_b64 s[28:29], -1, 0
	v_lshrrev_b32_e32 v3, 2, v196
	s_lshl_b32 s33, s58, 6
	v_add_u32_e32 v31, v1, v2
	s_mov_b32 s47, s35
	v_add_u32_e32 v23, 16, v148
	v_add_u32_e32 v24, 32, v148
	v_add_u32_e32 v25, 48, v148
	v_lshl_add_u64 v[10:11], s[52:53], 0, v[8:9]
	v_lshl_add_u64 v[12:13], s[64:65], 0, v[8:9]
	v_lshl_add_u64 v[14:15], s[50:51], 0, v[8:9]
	v_mov_b32_e32 v149, v9
	s_lshl_b32 s11, s12, 6
	s_mov_b32 s14, 0xfffec000
	v_or_b32_e32 v28, 0xfffec000, v3
	s_movk_i32 s15, 0xc000
	s_addk_i32 s33, 0xc000
	s_add_i32 s35, s12, 0xfffffb00
	s_mov_b32 s40, 0xffff4000
	v_or_b32_e32 v29, 0xffff4000, v3
	s_add_i32 s41, s12, 0xfffffd00
	v_or_b32_e32 v30, 0xffffc000, v3
	s_mov_b32 s37, 0
	v_add_u32_e32 v32, 0x1040, v31
	v_add_u32_e32 v33, 0x1048, v31
	v_add_u32_e32 v34, 0x2080, v31
	v_add_u32_e32 v35, 0x2088, v31
	v_add_u32_e32 v36, 0x30c0, v31
	v_add_u32_e32 v37, 0x30c8, v31
	v_add_u32_e32 v38, 0x400, v26
	v_add_u32_e32 v39, 0x400, v27
	v_add_u32_e32 v40, 0x800, v26
	v_add_u32_e32 v41, 0x800, v27
	v_add_u32_e32 v42, 0xc00, v26
	v_add_u32_e32 v43, 0xc00, v27
	v_lshlrev_b32_e32 v16, 1, v0
	s_branch .LBB0_697

.LBB0_696:
	s_add_i32 s35, s35, s10
	s_add_i32 s14, s14, s33
	s_add_i32 s41, s41, s10
	s_add_i32 s40, s40, s33
	s_add_i32 s2, s35, 0x920
	s_add_i32 s15, s15, s33
	v_add_u32_e32 v28, s33, v28
	v_add_u32_e32 v29, s33, v29
	s_cmpk_lt_i32 s2, 0x920
	v_add_u32_e32 v30, s33, v30
	s_cbranch_scc0 .LBB0_725
